# GEMM2 epilogue: residual chunks fetched one 4-chunk batch ahead (vmcnt(0)-only waits); LN modulation batch uses one full wait; scan loop-head vmcnt relaxation removed
# speedup vs baseline: 1.0086x; 1.0086x over previous
;     __device__ __forceinline__ void operator()(const f32x4 (&acc)[2][2][4][2], const pg8::Unit& u, int wr, int wc, int fr, int fq) const {
;     ...
;         const int col0 = u.pn * 256 + wc * 32 + 4 * fq;
;         f32x4 gv[2][2];
; #pragma unroll
;         for (int bj = 0; bj < 2; ++bj)
; #pragma unroll
;             for (int n = 0; n < 2; ++n) gv[bj][n] = *(const f32x4*)(gate + col0 + bj * 128 + n * 16);
; #pragma unroll
;         for (int ai = 0; ai < 2; ++ai)
; #pragma unroll
;             for (int m = 0; m < 4; ++m) { const size_t ro = (size_t)(wr * 64 + fr + ai * 128 + m * 16) * D + col0;
; #pragma unroll
;                 for (int bj = 0; bj < 2; ++bj)
; #pragma unroll
;                     for (int n = 0; n < 2; ++n) { const f32x4 xv = *(const f32x4*)(xr + ro + bj * 128 + n * 16);
;                         *(f32x4*)(ds + ro + bj * 128 + n * 16) = xv * ALPHA + gv[bj][n] * acc[ai][bj][m][n]; } }
.LBB0_326:
	s_add_u32 s22, s28, s24
	s_addc_u32 s23, s29, s25
	s_lshl_b64 s[24:25], s[26:27], 2
	v_lshl_or_b32 v176, s68, 8, v179
	s_add_u32 s24, s56, s24
	v_ashrrev_i32_e32 v177, 31, v176
	s_addc_u32 s25, s57, s25
	v_lshl_add_u64 v[132:133], v[152:153], 0, v[176:177]
	v_lshl_add_u64 v[128:129], v[176:177], 2, s[24:25]
	s_mov_b32 s17, 0x32434000
	v_lshlrev_b64 v[132:133], 2, v[132:133]
	v_add_co_u32_e32 v130, vcc, s17, v128
	v_lshl_add_u64 v[186:187], s[22:23], 0, v[132:133]
	v_addc_co_u32_e32 v131, vcc, 0, v129, vcc
	global_load_dwordx4 v[140:143], v[130:131], off
	s_mov_b64 s[24:25], 0x32434000
	v_lshl_add_u64 v[188:189], s[8:9], 0, v[132:133]
	v_lshl_add_u64 v[128:129], v[128:129], 0, s[24:25]
	global_load_dwordx4 v[136:139], v[128:129], off offset:64
	global_load_dwordx4 v[132:135], v[128:129], off offset:512
	s_nop 0
	global_load_dwordx4 v[128:131], v[128:129], off offset:576
	v_lshl_add_u64 v[194:195], v[152:153], 0, v[176:177]
	v_lshlrev_b64 v[194:195], 2, v[194:195]
	v_lshl_add_u64 v[196:197], s[22:23], 0, v[194:195]
	global_load_dwordx4 v[224:227], v[196:197], off
	global_load_dwordx4 v[228:231], v[196:197], off offset:64
	global_load_dwordx4 v[232:235], v[196:197], off offset:512
	global_load_dwordx4 v[236:239], v[196:197], off offset:576
	s_mov_b32 s68, s16
	s_mov_b32 s28, s67
	s_mov_b64 s[24:25], s[20:21]
	s_and_b64 vcc, exec, s[6:7]
	s_waitcnt vmcnt(0)
	v_lshl_add_u64 v[194:195], v[158:159], 0, v[176:177]
	v_lshlrev_b64 v[194:195], 2, v[194:195]
	v_lshl_add_u64 v[196:197], s[22:23], 0, v[194:195]
	global_load_dwordx4 v[240:243], v[196:197], off
	global_load_dwordx4 v[244:247], v[196:197], off offset:64
	global_load_dwordx4 v[248:251], v[196:197], off offset:512
	global_load_dwordx4 v[190:193], v[196:197], off offset:576
	v_pk_mul_f32 v[184:185], v[226:227], s[50:51] op_sel_hi:[1,0]
	v_pk_mul_f32 v[182:183], v[224:225], s[50:51] op_sel_hi:[1,0]
	v_pk_fma_f32 v[126:127], v[126:127], v[142:143], v[184:185]
	v_pk_fma_f32 v[124:125], v[124:125], v[140:141], v[182:183]
	global_store_dwordx4 v[188:189], v[124:127], off
	s_nop 1
	v_pk_mul_f32 v[126:127], v[230:231], s[50:51] op_sel_hi:[1,0]
	v_pk_mul_f32 v[124:125], v[228:229], s[50:51] op_sel_hi:[1,0]
	v_pk_fma_f32 v[122:123], v[122:123], v[138:139], v[126:127]
	v_pk_fma_f32 v[120:121], v[120:121], v[136:137], v[124:125]
	global_store_dwordx4 v[188:189], v[120:123], off offset:64
	s_nop 1
	v_pk_mul_f32 v[122:123], v[234:235], s[50:51] op_sel_hi:[1,0]
	v_pk_mul_f32 v[120:121], v[232:233], s[50:51] op_sel_hi:[1,0]
	v_pk_fma_f32 v[118:119], v[118:119], v[134:135], v[122:123]
	v_pk_fma_f32 v[116:117], v[116:117], v[132:133], v[120:121]
	global_store_dwordx4 v[188:189], v[116:119], off offset:512
	s_nop 1
	v_lshl_add_u64 v[120:121], v[158:159], 0, v[176:177]
	v_lshlrev_b64 v[120:121], 2, v[120:121]
	v_lshl_add_u64 v[122:123], s[22:23], 0, v[120:121]
	v_pk_mul_f32 v[118:119], v[238:239], s[50:51] op_sel_hi:[1,0]
	v_pk_mul_f32 v[116:117], v[236:237], s[50:51] op_sel_hi:[1,0]
	v_pk_fma_f32 v[110:111], v[110:111], v[130:131], v[118:119]
	v_pk_fma_f32 v[108:109], v[108:109], v[128:129], v[116:117]
	global_store_dwordx4 v[188:189], v[108:111], off offset:576
	s_nop 1
	v_lshl_add_u64 v[116:117], s[8:9], 0, v[120:121]
	s_waitcnt vmcnt(0)
	v_lshl_add_u64 v[194:195], v[160:161], 0, v[176:177]
	v_lshlrev_b64 v[194:195], 2, v[194:195]
	v_lshl_add_u64 v[196:197], s[22:23], 0, v[194:195]
	global_load_dwordx4 v[224:227], v[196:197], off
	global_load_dwordx4 v[228:231], v[196:197], off offset:64
	global_load_dwordx4 v[232:235], v[196:197], off offset:512
	global_load_dwordx4 v[236:239], v[196:197], off offset:576
	v_pk_mul_f32 v[110:111], v[242:243], s[50:51] op_sel_hi:[1,0]
	v_pk_mul_f32 v[108:109], v[240:241], s[50:51] op_sel_hi:[1,0]
	v_pk_fma_f32 v[110:111], v[114:115], v[142:143], v[110:111]
	v_pk_fma_f32 v[108:109], v[112:113], v[140:141], v[108:109]
	global_store_dwordx4 v[116:117], v[108:111], off
	s_nop 1
	v_pk_mul_f32 v[110:111], v[246:247], s[50:51] op_sel_hi:[1,0]
	v_pk_mul_f32 v[108:109], v[244:245], s[50:51] op_sel_hi:[1,0]
	v_pk_fma_f32 v[106:107], v[106:107], v[138:139], v[110:111]
	v_pk_fma_f32 v[104:105], v[104:105], v[136:137], v[108:109]
	global_store_dwordx4 v[116:117], v[104:107], off offset:64
	s_nop 1
	v_pk_mul_f32 v[106:107], v[250:251], s[50:51] op_sel_hi:[1,0]
	v_pk_mul_f32 v[104:105], v[248:249], s[50:51] op_sel_hi:[1,0]
	v_pk_fma_f32 v[102:103], v[102:103], v[134:135], v[106:107]
	v_pk_fma_f32 v[100:101], v[100:101], v[132:133], v[104:105]
	global_store_dwordx4 v[116:117], v[100:103], off offset:512
	s_nop 1
	v_lshl_add_u64 v[104:105], v[160:161], 0, v[176:177]
	v_lshlrev_b64 v[104:105], 2, v[104:105]
	v_lshl_add_u64 v[106:107], s[22:23], 0, v[104:105]
	v_pk_mul_f32 v[102:103], v[192:193], s[50:51] op_sel_hi:[1,0]
	v_pk_mul_f32 v[100:101], v[190:191], s[50:51] op_sel_hi:[1,0]
	v_pk_fma_f32 v[94:95], v[94:95], v[130:131], v[102:103]
	v_pk_fma_f32 v[92:93], v[92:93], v[128:129], v[100:101]
	global_store_dwordx4 v[116:117], v[92:95], off offset:576
	s_nop 1
	v_lshl_add_u64 v[100:101], s[8:9], 0, v[104:105]
	s_waitcnt vmcnt(0)
;     __device__ __forceinline__ void operator()(const f32x4 (&acc)[2][2][4][2], const pg8::Unit& u, int wr, int wc, int fr, int fq) const {
;     ...
;         for (int ai = 0; ai < 2; ++ai)
; #pragma unroll
;             for (int m = 0; m < 4; ++m) { const size_t ro = (size_t)(wr * 64 + fr + ai * 128 + m * 16) * D + col0;
; #pragma unroll
;                 for (int bj = 0; bj < 2; ++bj)
; #pragma unroll
;                     for (int n = 0; n < 2; ++n) { const f32x4 xv = *(const f32x4*)(xr + ro + bj * 128 + n * 16);
;                         *(f32x4*)(ds + ro + bj * 128 + n * 16) = xv * ALPHA + gv[bj][n] * acc[ai][bj][m][n]; } }
	v_lshl_add_u64 v[194:195], v[162:163], 0, v[176:177]
	v_lshlrev_b64 v[194:195], 2, v[194:195]
	v_lshl_add_u64 v[196:197], s[22:23], 0, v[194:195]
	global_load_dwordx4 v[240:243], v[196:197], off
	global_load_dwordx4 v[244:247], v[196:197], off offset:64
	global_load_dwordx4 v[248:251], v[196:197], off offset:512
	global_load_dwordx4 v[190:193], v[196:197], off offset:576
	v_pk_mul_f32 v[94:95], v[226:227], s[50:51] op_sel_hi:[1,0]
	v_pk_mul_f32 v[92:93], v[224:225], s[50:51] op_sel_hi:[1,0]
	v_pk_fma_f32 v[94:95], v[98:99], v[142:143], v[94:95]
	v_pk_fma_f32 v[92:93], v[96:97], v[140:141], v[92:93]
	global_store_dwordx4 v[100:101], v[92:95], off
	s_nop 1
	v_pk_mul_f32 v[94:95], v[230:231], s[50:51] op_sel_hi:[1,0]
	v_pk_mul_f32 v[92:93], v[228:229], s[50:51] op_sel_hi:[1,0]
	v_pk_fma_f32 v[90:91], v[90:91], v[138:139], v[94:95]
	v_pk_fma_f32 v[88:89], v[88:89], v[136:137], v[92:93]
	global_store_dwordx4 v[100:101], v[88:91], off offset:64
	s_nop 1
	v_pk_mul_f32 v[90:91], v[234:235], s[50:51] op_sel_hi:[1,0]
	v_pk_mul_f32 v[88:89], v[232:233], s[50:51] op_sel_hi:[1,0]
	v_pk_fma_f32 v[86:87], v[86:87], v[134:135], v[90:91]
	v_pk_fma_f32 v[84:85], v[84:85], v[132:133], v[88:89]
	global_store_dwordx4 v[100:101], v[84:87], off offset:512
	s_nop 1
	v_lshl_add_u64 v[88:89], v[162:163], 0, v[176:177]
	v_lshlrev_b64 v[88:89], 2, v[88:89]
	v_lshl_add_u64 v[90:91], s[22:23], 0, v[88:89]
	v_pk_mul_f32 v[86:87], v[238:239], s[50:51] op_sel_hi:[1,0]
	v_pk_mul_f32 v[84:85], v[236:237], s[50:51] op_sel_hi:[1,0]
	v_pk_fma_f32 v[78:79], v[78:79], v[130:131], v[86:87]
	v_pk_fma_f32 v[76:77], v[76:77], v[128:129], v[84:85]
	global_store_dwordx4 v[100:101], v[76:79], off offset:576
	s_nop 1
	v_lshl_add_u64 v[84:85], s[8:9], 0, v[88:89]
	s_waitcnt vmcnt(0)
	v_lshl_add_u64 v[194:195], v[164:165], 0, v[176:177]
	v_lshlrev_b64 v[194:195], 2, v[194:195]
	v_lshl_add_u64 v[196:197], s[22:23], 0, v[194:195]
	global_load_dwordx4 v[224:227], v[196:197], off
	global_load_dwordx4 v[228:231], v[196:197], off offset:64
	global_load_dwordx4 v[232:235], v[196:197], off offset:512
	global_load_dwordx4 v[236:239], v[196:197], off offset:576
	v_pk_mul_f32 v[78:79], v[242:243], s[50:51] op_sel_hi:[1,0]
	v_pk_mul_f32 v[76:77], v[240:241], s[50:51] op_sel_hi:[1,0]
	v_pk_fma_f32 v[78:79], v[82:83], v[142:143], v[78:79]
	v_pk_fma_f32 v[76:77], v[80:81], v[140:141], v[76:77]
	global_store_dwordx4 v[84:85], v[76:79], off
	s_nop 1
	v_pk_mul_f32 v[78:79], v[246:247], s[50:51] op_sel_hi:[1,0]
	v_pk_mul_f32 v[76:77], v[244:245], s[50:51] op_sel_hi:[1,0]
	v_pk_fma_f32 v[74:75], v[74:75], v[138:139], v[78:79]
	v_pk_fma_f32 v[72:73], v[72:73], v[136:137], v[76:77]
	global_store_dwordx4 v[84:85], v[72:75], off offset:64
	s_nop 1
	v_pk_mul_f32 v[74:75], v[250:251], s[50:51] op_sel_hi:[1,0]
	v_pk_mul_f32 v[72:73], v[248:249], s[50:51] op_sel_hi:[1,0]
	v_pk_fma_f32 v[70:71], v[70:71], v[134:135], v[74:75]
	v_pk_fma_f32 v[68:69], v[68:69], v[132:133], v[72:73]
	global_store_dwordx4 v[84:85], v[68:71], off offset:512
	s_nop 1
	v_lshl_add_u64 v[72:73], v[164:165], 0, v[176:177]
	v_lshlrev_b64 v[72:73], 2, v[72:73]
	v_lshl_add_u64 v[74:75], s[22:23], 0, v[72:73]
	v_pk_mul_f32 v[70:71], v[192:193], s[50:51] op_sel_hi:[1,0]
	v_pk_mul_f32 v[68:69], v[190:191], s[50:51] op_sel_hi:[1,0]
	v_pk_fma_f32 v[66:67], v[66:67], v[130:131], v[70:71]
	v_pk_fma_f32 v[64:65], v[64:65], v[128:129], v[68:69]
	global_store_dwordx4 v[84:85], v[64:67], off offset:576
	s_nop 1
	v_lshl_add_u64 v[68:69], s[8:9], 0, v[72:73]
	s_waitcnt vmcnt(0)
	v_lshl_add_u64 v[194:195], v[166:167], 0, v[176:177]
	v_lshlrev_b64 v[194:195], 2, v[194:195]
	v_lshl_add_u64 v[196:197], s[22:23], 0, v[194:195]
	global_load_dwordx4 v[240:243], v[196:197], off
	global_load_dwordx4 v[244:247], v[196:197], off offset:64
	global_load_dwordx4 v[248:251], v[196:197], off offset:512
	global_load_dwordx4 v[190:193], v[196:197], off offset:576
	v_pk_mul_f32 v[66:67], v[226:227], s[50:51] op_sel_hi:[1,0]
	v_pk_mul_f32 v[64:65], v[224:225], s[50:51] op_sel_hi:[1,0]
	v_pk_fma_f32 v[62:63], v[62:63], v[142:143], v[66:67]
	v_pk_fma_f32 v[60:61], v[60:61], v[140:141], v[64:65]
	global_store_dwordx4 v[68:69], v[60:63], off
	s_nop 1
	v_pk_mul_f32 v[62:63], v[230:231], s[50:51] op_sel_hi:[1,0]
	v_pk_mul_f32 v[60:61], v[228:229], s[50:51] op_sel_hi:[1,0]
	v_pk_fma_f32 v[58:59], v[58:59], v[138:139], v[62:63]
	v_pk_fma_f32 v[56:57], v[56:57], v[136:137], v[60:61]
	global_store_dwordx4 v[68:69], v[56:59], off offset:64
	s_nop 1
	v_pk_mul_f32 v[58:59], v[234:235], s[50:51] op_sel_hi:[1,0]
	v_pk_mul_f32 v[56:57], v[232:233], s[50:51] op_sel_hi:[1,0]
	v_pk_fma_f32 v[54:55], v[54:55], v[134:135], v[58:59]
	v_pk_fma_f32 v[52:53], v[52:53], v[132:133], v[56:57]
	global_store_dwordx4 v[68:69], v[52:55], off offset:512
	s_nop 1
	v_lshl_add_u64 v[56:57], v[166:167], 0, v[176:177]
	v_lshlrev_b64 v[56:57], 2, v[56:57]
	v_lshl_add_u64 v[58:59], s[22:23], 0, v[56:57]
	v_pk_mul_f32 v[54:55], v[238:239], s[50:51] op_sel_hi:[1,0]
	v_pk_mul_f32 v[52:53], v[236:237], s[50:51] op_sel_hi:[1,0]
	v_pk_fma_f32 v[46:47], v[46:47], v[130:131], v[54:55]
	v_pk_fma_f32 v[44:45], v[44:45], v[128:129], v[52:53]
	global_store_dwordx4 v[68:69], v[44:47], off offset:576
	s_nop 1
	v_lshl_add_u64 v[52:53], s[8:9], 0, v[56:57]
	s_waitcnt vmcnt(0)
;     __device__ __forceinline__ void operator()(const f32x4 (&acc)[2][2][4][2], const pg8::Unit& u, int wr, int wc, int fr, int fq) const {
;     ...
;         for (int ai = 0; ai < 2; ++ai)
; #pragma unroll
;             for (int m = 0; m < 4; ++m) { const size_t ro = (size_t)(wr * 64 + fr + ai * 128 + m * 16) * D + col0;
; #pragma unroll
;                 for (int bj = 0; bj < 2; ++bj)
; #pragma unroll
;                     for (int n = 0; n < 2; ++n) { const f32x4 xv = *(const f32x4*)(xr + ro + bj * 128 + n * 16);
;                         *(f32x4*)(ds + ro + bj * 128 + n * 16) = xv * ALPHA + gv[bj][n] * acc[ai][bj][m][n]; } }
	v_lshl_add_u64 v[194:195], v[168:169], 0, v[176:177]
	v_lshlrev_b64 v[194:195], 2, v[194:195]
	v_lshl_add_u64 v[196:197], s[22:23], 0, v[194:195]
	global_load_dwordx4 v[224:227], v[196:197], off
	global_load_dwordx4 v[228:231], v[196:197], off offset:64
	global_load_dwordx4 v[232:235], v[196:197], off offset:512
	global_load_dwordx4 v[236:239], v[196:197], off offset:576
	v_pk_mul_f32 v[46:47], v[242:243], s[50:51] op_sel_hi:[1,0]
	v_pk_mul_f32 v[44:45], v[240:241], s[50:51] op_sel_hi:[1,0]
	v_pk_fma_f32 v[46:47], v[50:51], v[142:143], v[46:47]
	v_pk_fma_f32 v[44:45], v[48:49], v[140:141], v[44:45]
	global_store_dwordx4 v[52:53], v[44:47], off
	s_nop 1
	v_pk_mul_f32 v[46:47], v[246:247], s[50:51] op_sel_hi:[1,0]
	v_pk_mul_f32 v[44:45], v[244:245], s[50:51] op_sel_hi:[1,0]
	v_pk_fma_f32 v[42:43], v[42:43], v[138:139], v[46:47]
	v_pk_fma_f32 v[40:41], v[40:41], v[136:137], v[44:45]
	global_store_dwordx4 v[52:53], v[40:43], off offset:64
	s_nop 1
	v_pk_mul_f32 v[42:43], v[250:251], s[50:51] op_sel_hi:[1,0]
	v_pk_mul_f32 v[40:41], v[248:249], s[50:51] op_sel_hi:[1,0]
	v_pk_fma_f32 v[38:39], v[38:39], v[134:135], v[42:43]
	v_pk_fma_f32 v[36:37], v[36:37], v[132:133], v[40:41]
	global_store_dwordx4 v[52:53], v[36:39], off offset:512
	s_nop 1
	v_lshl_add_u64 v[40:41], v[168:169], 0, v[176:177]
	v_lshlrev_b64 v[40:41], 2, v[40:41]
	v_lshl_add_u64 v[42:43], s[22:23], 0, v[40:41]
	v_pk_mul_f32 v[38:39], v[192:193], s[50:51] op_sel_hi:[1,0]
	v_pk_mul_f32 v[36:37], v[190:191], s[50:51] op_sel_hi:[1,0]
	v_pk_fma_f32 v[30:31], v[30:31], v[130:131], v[38:39]
	v_pk_fma_f32 v[28:29], v[28:29], v[128:129], v[36:37]
	global_store_dwordx4 v[52:53], v[28:31], off offset:576
	s_nop 1
	v_lshl_add_u64 v[36:37], s[8:9], 0, v[40:41]
	s_waitcnt vmcnt(0)
	v_lshl_add_u64 v[194:195], v[170:171], 0, v[176:177]
	v_lshlrev_b64 v[194:195], 2, v[194:195]
	v_lshl_add_u64 v[196:197], s[22:23], 0, v[194:195]
	global_load_dwordx4 v[240:243], v[196:197], off
	global_load_dwordx4 v[244:247], v[196:197], off offset:64
	global_load_dwordx4 v[248:251], v[196:197], off offset:512
	global_load_dwordx4 v[190:193], v[196:197], off offset:576
	v_pk_mul_f32 v[30:31], v[226:227], s[50:51] op_sel_hi:[1,0]
	v_pk_mul_f32 v[28:29], v[224:225], s[50:51] op_sel_hi:[1,0]
	v_pk_fma_f32 v[30:31], v[34:35], v[142:143], v[30:31]
	v_pk_fma_f32 v[28:29], v[32:33], v[140:141], v[28:29]
	global_store_dwordx4 v[36:37], v[28:31], off
	s_nop 1
	v_pk_mul_f32 v[30:31], v[230:231], s[50:51] op_sel_hi:[1,0]
	v_pk_mul_f32 v[28:29], v[228:229], s[50:51] op_sel_hi:[1,0]
	v_pk_fma_f32 v[26:27], v[26:27], v[138:139], v[30:31]
	v_pk_fma_f32 v[24:25], v[24:25], v[136:137], v[28:29]
	global_store_dwordx4 v[36:37], v[24:27], off offset:64
	s_nop 1
	v_pk_mul_f32 v[26:27], v[234:235], s[50:51] op_sel_hi:[1,0]
	v_pk_mul_f32 v[24:25], v[232:233], s[50:51] op_sel_hi:[1,0]
	v_pk_fma_f32 v[22:23], v[22:23], v[134:135], v[26:27]
	v_pk_fma_f32 v[20:21], v[20:21], v[132:133], v[24:25]
	global_store_dwordx4 v[36:37], v[20:23], off offset:512
	s_nop 1
	v_lshl_add_u64 v[24:25], v[170:171], 0, v[176:177]
	v_lshlrev_b64 v[24:25], 2, v[24:25]
	v_lshl_add_u64 v[26:27], s[22:23], 0, v[24:25]
	s_mov_b64 s[22:23], s[18:19]
	v_pk_mul_f32 v[22:23], v[238:239], s[50:51] op_sel_hi:[1,0]
	v_pk_mul_f32 v[20:21], v[236:237], s[50:51] op_sel_hi:[1,0]
	v_pk_fma_f32 v[14:15], v[14:15], v[130:131], v[22:23]
	v_pk_fma_f32 v[12:13], v[12:13], v[128:129], v[20:21]
	global_store_dwordx4 v[36:37], v[12:15], off offset:576
	s_nop 1
	v_lshl_add_u64 v[20:21], s[8:9], 0, v[24:25]
	s_waitcnt vmcnt(0)
	v_pk_mul_f32 v[14:15], v[242:243], s[50:51] op_sel_hi:[1,0]
	v_pk_mul_f32 v[12:13], v[240:241], s[50:51] op_sel_hi:[1,0]
	v_pk_fma_f32 v[14:15], v[18:19], v[142:143], v[14:15]
	v_pk_fma_f32 v[12:13], v[16:17], v[140:141], v[12:13]
	global_store_dwordx4 v[20:21], v[12:15], off
	s_nop 1
	v_pk_mul_f32 v[14:15], v[246:247], s[50:51] op_sel_hi:[1,0]
	v_pk_mul_f32 v[12:13], v[244:245], s[50:51] op_sel_hi:[1,0]
	v_pk_fma_f32 v[10:11], v[10:11], v[138:139], v[14:15]
	v_pk_fma_f32 v[8:9], v[8:9], v[136:137], v[12:13]
	global_store_dwordx4 v[20:21], v[8:11], off offset:64
	s_nop 1
	v_pk_mul_f32 v[10:11], v[250:251], s[50:51] op_sel_hi:[1,0]
	v_pk_mul_f32 v[8:9], v[248:249], s[50:51] op_sel_hi:[1,0]
	v_pk_fma_f32 v[6:7], v[6:7], v[134:135], v[10:11]
	v_pk_fma_f32 v[4:5], v[4:5], v[132:133], v[8:9]
	global_store_dwordx4 v[20:21], v[4:7], off offset:512
	s_nop 1
	v_pk_mul_f32 v[6:7], v[192:193], s[50:51] op_sel_hi:[1,0]
	v_pk_mul_f32 v[4:5], v[190:191], s[50:51] op_sel_hi:[1,0]
	v_pk_fma_f32 v[2:3], v[2:3], v[130:131], v[6:7]
	v_pk_fma_f32 v[0:1], v[0:1], v[128:129], v[4:5]
	global_store_dwordx4 v[20:21], v[0:3], off offset:576
	s_nop 1
	s_cbranch_vccnz .LBB0_337

; __device__ __forceinline__ void row_stats(const f32x4 (&v)[8], float& mean, float& rstd) {
;     float s = 0.f;
; #pragma unroll
;     for (int i = 0; i < 8; ++i) s += v[i][0] + v[i][1] + v[i][2] + v[i][3];
;     mean = wsum(s) * (1.f / 2048.f);
;     float q = 0.f;
; #pragma unroll
;     for (int i = 0; i < 8; ++i) { const f32x4 d = v[i] - mean; q += d[0] * d[0] + d[1] * d[1] + d[2] * d[2] + d[3] * d[3]; }
;     rstd = rsqrtf(wsum(q) * (1.f / 2048.f) + LN_EPS);
; __device__ void phase_ln(const Params& p, int l) {
;     ...
;         row_stats(v, mean, rstd);
;         const float* md = p.MOD + (size_t)(l * 3 + (isctx ? 2 : b)) * 6144;
;         u16* ur = p.U + (size_t)row * 2048;
; #pragma unroll
;         for (int i = 0; i < 8; ++i) { const f32x4 sh = *(const f32x4*)(md + i * 256 + lane * 4), sc = *(const f32x4*)(md + 2048 + i * 256 + lane * 4);
.LBB0_352:
	s_andn2_b64 vcc, exec, s[22:23]
	s_cbranch_vccnz .LBB0_344
	s_waitcnt vmcnt(0)
	v_add_f32_e32 v35, v28, v29
	v_add_f32_e32 v35, v30, v35
	v_add_f32_e32 v61, v24, v25
	v_add_f32_e32 v35, v31, v35
	v_add_f32_e32 v61, v26, v61
	v_add_f32_e32 v35, 0, v35
	v_add_f32_e32 v61, v27, v61
	v_add_f32_e32 v35, v61, v35
	v_add_f32_e32 v61, v20, v21
	v_add_f32_e32 v61, v22, v61
	v_add_f32_e32 v61, v23, v61
	v_add_f32_e32 v35, v61, v35
	v_add_f32_e32 v61, v16, v17
	v_mov_b32_e32 v62, v8
	v_mov_b32_e32 v63, v12
	v_mov_b32_e32 v64, v9
	v_mov_b32_e32 v65, v13
	v_add_f32_e32 v61, v18, v61
	v_pk_add_f32 v[62:63], v[62:63], v[64:65]
	v_mov_b32_e32 v64, v10
	v_mov_b32_e32 v65, v14
	v_add_f32_e32 v61, v19, v61
	v_pk_add_f32 v[62:63], v[64:65], v[62:63]
	v_mov_b32_e32 v64, v11
	v_mov_b32_e32 v65, v15
	v_add_f32_e32 v35, v61, v35
	v_pk_add_f32 v[62:63], v[64:65], v[62:63]
	v_mov_b32_e32 v64, v1
	v_add_f32_e32 v35, v63, v35
	v_add_f32_e32 v35, v62, v35
	v_mov_b32_e32 v62, v0
	v_mov_b32_e32 v63, v4
	v_mov_b32_e32 v65, v5
	v_pk_add_f32 v[62:63], v[62:63], v[64:65]
	v_mov_b32_e32 v64, v2
	v_mov_b32_e32 v65, v6
	v_pk_add_f32 v[62:63], v[64:65], v[62:63]
	v_mov_b32_e32 v64, v3
	v_mov_b32_e32 v65, v7
	v_pk_add_f32 v[62:63], v[64:65], v[62:63]
	v_cmp_lt_i32_e32 vcc, v211, v210
	v_add_f32_e32 v35, v63, v35
	v_add_f32_e32 v35, v62, v35
	v_cndmask_b32_e32 v61, v208, v211, vcc
	v_lshlrev_b32_e32 v82, 2, v61
	ds_bpermute_b32 v61, v82, v35
	v_cmp_lt_i32_e32 vcc, v212, v210
	v_lshrrev_b32_e32 v60, 13, v60
	v_cndmask_b32_e64 v60, v60, 2, s[6:7]
	s_waitcnt lgkmcnt(0)
	v_add_f32_e32 v35, v35, v61
	v_cndmask_b32_e32 v61, v208, v212, vcc
	v_lshlrev_b32_e32 v83, 2, v61
	ds_bpermute_b32 v61, v83, v35
	v_cmp_lt_i32_e32 vcc, v213, v210
	s_waitcnt lgkmcnt(0)
	v_add_f32_e32 v35, v35, v61
	v_cndmask_b32_e32 v61, v208, v213, vcc
	v_lshlrev_b32_e32 v84, 2, v61
	ds_bpermute_b32 v61, v84, v35
	v_cmp_lt_i32_e32 vcc, v214, v210
	s_waitcnt lgkmcnt(0)
	v_add_f32_e32 v35, v35, v61
	v_cndmask_b32_e32 v61, v208, v214, vcc
	v_lshlrev_b32_e32 v85, 2, v61
	ds_bpermute_b32 v61, v85, v35
	v_cmp_lt_i32_e32 vcc, v215, v210
	s_waitcnt lgkmcnt(0)
	v_add_f32_e32 v35, v35, v61
	v_cndmask_b32_e32 v61, v208, v215, vcc
	v_lshlrev_b32_e32 v86, 2, v61
	ds_bpermute_b32 v61, v86, v35
	v_cmp_lt_i32_e32 vcc, v216, v210
	s_waitcnt lgkmcnt(0)
	v_add_f32_e32 v35, v35, v61
	v_cndmask_b32_e32 v61, v208, v216, vcc
	v_lshlrev_b32_e32 v87, 2, v61
	ds_bpermute_b32 v61, v87, v35
	s_waitcnt lgkmcnt(0)
	v_add_f32_e32 v35, v35, v61
	v_fmac_f32_e32 v29, 0xba000000, v35
	v_fmac_f32_e32 v25, 0xba000000, v35
	v_fmamk_f32 v28, v35, 0xba000000, v28
	v_mul_f32_e32 v61, v29, v29
	v_fmamk_f32 v68, v35, 0xba000000, v26
	v_fmamk_f32 v24, v35, 0xba000000, v24
	v_mul_f32_e32 v26, v25, v25
	v_fmac_f32_e32 v21, 0xba000000, v35
	v_fmamk_f32 v30, v35, 0xba000000, v30
	v_fmac_f32_e32 v61, v28, v28
	v_fmac_f32_e32 v26, v24, v24
	v_fmamk_f32 v70, v35, 0xba000000, v22
	v_fmamk_f32 v20, v35, 0xba000000, v20
	v_mul_f32_e32 v22, v21, v21
	v_fmac_f32_e32 v17, 0xba000000, v35
	v_fmamk_f32 v31, v35, 0xba000000, v31
	v_fmac_f32_e32 v61, v30, v30
	v_fmamk_f32 v69, v35, 0xba000000, v27
	v_fmac_f32_e32 v26, v68, v68
	v_fmac_f32_e32 v22, v20, v20
	v_fmamk_f32 v72, v35, 0xba000000, v18
	v_fmamk_f32 v16, v35, 0xba000000, v16
	v_mul_f32_e32 v18, v17, v17
	v_fmac_f32_e32 v61, v31, v31
	v_fmac_f32_e32 v26, v69, v69
	v_fmamk_f32 v71, v35, 0xba000000, v23
	v_fmac_f32_e32 v22, v70, v70
	v_fmac_f32_e32 v18, v16, v16
	v_add_f32_e32 v26, v61, v26
	v_fmac_f32_e32 v22, v71, v71
	v_fmamk_f32 v73, v35, 0xba000000, v19
	v_fmac_f32_e32 v18, v72, v72
	v_add_f32_e32 v22, v22, v26
	v_fmac_f32_e32 v18, v73, v73
	v_fmamk_f32 v13, v35, 0xba000000, v13
	v_fmamk_f32 v9, v35, 0xba000000, v9
	v_add_f32_e32 v26, v18, v22
	v_fmac_f32_e32 v12, 0xba000000, v35
	v_fmac_f32_e32 v8, 0xba000000, v35
	v_mov_b32_e32 v22, v9
	v_mov_b32_e32 v23, v13
	v_mov_b32_e32 v18, v8
	v_mov_b32_e32 v19, v12
	v_pk_mul_f32 v[22:23], v[22:23], v[22:23]
	v_add_u32_e32 v27, s44, v60
	v_pk_fma_f32 v[18:19], v[18:19], v[18:19], v[22:23]
	v_mov_b64_e32 v[22:23], s[16:17]
	v_mad_i64_i32 v[22:23], s[6:7], v27, s65, v[22:23]
	v_lshl_add_u64 v[74:75], v[22:23], 0, v[148:149]
	s_movk_i32 s6, 0x3000
	v_add_co_u32_e32 v76, vcc, s6, v74
	v_fmamk_f32 v14, v35, 0xba000000, v14
	s_nop 0
	v_addc_co_u32_e32 v77, vcc, 0, v75, vcc
	global_load_dwordx4 v[60:63], v[74:75], off
	global_load_dwordx4 v[64:67], v[76:77], off offset:-4096
	v_fmamk_f32 v10, v35, 0xba000000, v10
	v_fmamk_f32 v5, v35, 0xba000000, v5
	v_fmamk_f32 v1, v35, 0xba000000, v1
	v_fmamk_f32 v15, v35, 0xba000000, v15
	v_fmamk_f32 v11, v35, 0xba000000, v11
	v_mov_b32_e32 v22, v10
	v_mov_b32_e32 v23, v14
	v_fmamk_f32 v79, v35, 0xba000000, v7
	v_fmamk_f32 v78, v35, 0xba000000, v6
	v_fmac_f32_e32 v4, 0xba000000, v35
	v_fmac_f32_e32 v0, 0xba000000, v35
	v_mov_b32_e32 v6, v1
	v_mov_b32_e32 v7, v5
	v_pk_fma_f32 v[18:19], v[22:23], v[22:23], v[18:19]
	v_mov_b32_e32 v22, v11
	v_mov_b32_e32 v23, v15
	v_fmamk_f32 v81, v35, 0xba000000, v3
	v_fmamk_f32 v80, v35, 0xba000000, v2
	v_mov_b32_e32 v2, v0
	v_mov_b32_e32 v3, v4
	v_pk_mul_f32 v[6:7], v[6:7], v[6:7]
	v_pk_fma_f32 v[18:19], v[22:23], v[22:23], v[18:19]
	v_pk_fma_f32 v[2:3], v[2:3], v[2:3], v[6:7]
	v_mov_b32_e32 v6, v80
	v_mov_b32_e32 v7, v78
	v_add_f32_e32 v19, v19, v26
	v_pk_fma_f32 v[2:3], v[6:7], v[6:7], v[2:3]
	v_mov_b32_e32 v6, v81
	v_mov_b32_e32 v7, v79
	v_add_f32_e32 v18, v18, v19
	v_pk_fma_f32 v[2:3], v[6:7], v[6:7], v[2:3]
	s_mov_b64 s[6:7], 0x2000
	v_add_f32_e32 v3, v3, v18
	v_add_f32_e32 v2, v2, v3
	ds_bpermute_b32 v3, v82, v2
	s_waitcnt lgkmcnt(0)
	v_add_f32_e32 v2, v2, v3
	ds_bpermute_b32 v3, v83, v2
	s_waitcnt lgkmcnt(0)
; __device__ __forceinline__ unsigned pk2(float lo, float hi) { const f32x2_t v = {lo, hi}; return __builtin_bit_cast(unsigned, __builtin_convertvector(v, bf16x2_t)); }
; __device__ void phase_ln(const Params& p, int l) {
;     ...
;         const float* md = p.MOD + (size_t)(l * 3 + (isctx ? 2 : b)) * 6144;
;         u16* ur = p.U + (size_t)row * 2048;
; #pragma unroll
;         for (int i = 0; i < 8; ++i) { const f32x4 sh = *(const f32x4*)(md + i * 256 + lane * 4), sc = *(const f32x4*)(md + 2048 + i * 256 + lane * 4);
;             const f32x4 o = (v[i] - mean) * rstd * (sc + 1.f) + sh;
;             u32x2 w; w.x = pk2(o[0], o[1]); w.y = pk2(o[2], o[3]);
;             *(u32x2*)(ur + i * 256 + lane * 4) = w; }
	v_add_f32_e32 v2, v2, v3
	ds_bpermute_b32 v3, v84, v2
	s_waitcnt lgkmcnt(0)
	v_add_f32_e32 v2, v2, v3
	ds_bpermute_b32 v3, v85, v2
	s_waitcnt lgkmcnt(0)
	v_add_f32_e32 v2, v2, v3
	ds_bpermute_b32 v3, v86, v2
	s_waitcnt lgkmcnt(0)
	v_add_f32_e32 v2, v2, v3
	ds_bpermute_b32 v3, v87, v2
	s_waitcnt lgkmcnt(0)
	v_add_f32_e32 v2, v2, v3
	v_fmamk_f32 v2, v2, 0x3a000000, v207
	v_mul_f32_e32 v3, 0x4b800000, v2
	v_cmp_gt_f32_e32 vcc, s41, v2
	s_waitcnt vmcnt(0)
	v_pk_add_f32 v[22:23], v[66:67], 1.0 op_sel_hi:[1,0]
	v_cndmask_b32_e32 v2, v2, v3, vcc
	v_rsq_f32_e32 v2, v2
	v_pk_add_f32 v[26:27], v[64:65], 1.0 op_sel_hi:[1,0]
	v_mul_f32_e32 v3, 0x45800000, v2
	v_cndmask_b32_e32 v82, v2, v3, vcc
	v_pk_mul_f32 v[6:7], v[28:29], v[82:83] op_sel_hi:[1,0]
	v_pk_mul_f32 v[18:19], v[30:31], v[82:83] op_sel_hi:[1,0]
	v_pk_fma_f32 v[6:7], v[26:27], v[6:7], v[60:61]
	v_pk_fma_f32 v[18:19], v[22:23], v[18:19], v[62:63]
	v_cvt_pk_bf16_f32 v6, v6, v7
	v_cvt_pk_bf16_f32 v7, v18, v19
	v_lshl_add_u64 v[2:3], v[74:75], 0, s[6:7]
	global_store_dwordx2 v[56:57], v[6:7], off
	v_add_co_u32_e32 v232, vcc, s69, v74
	global_load_dwordx4 v[158:161], v[2:3], off offset:1024
	global_load_dwordx4 v[162:165], v[74:75], off offset:1024
	v_addc_co_u32_e32 v233, vcc, 0, v75, vcc
	global_load_dwordx4 v[166:169], v[2:3], off offset:2048
	global_load_dwordx4 v[170:173], v[74:75], off offset:2048
	global_load_dwordx4 v[174:177], v[2:3], off offset:3072
	global_load_dwordx4 v[178:181], v[74:75], off offset:3072
	global_load_dwordx4 v[182:185], v[76:77], off
	global_load_dwordx4 v[186:189], v[232:233], off
	global_load_dwordx4 v[190:193], v[76:77], off offset:1024
	global_load_dwordx4 v[194:197], v[232:233], off offset:1024
	global_load_dwordx4 v[198:201], v[76:77], off offset:2048
	global_load_dwordx4 v[202:205], v[232:233], off offset:2048
	global_load_dwordx4 v[224:227], v[76:77], off offset:3072
	global_load_dwordx4 v[228:231], v[232:233], off offset:3072
	v_pk_mul_f32 v[6:7], v[24:25], v[82:83] op_sel_hi:[1,0]
	v_pk_mul_f32 v[18:19], v[68:69], v[82:83] op_sel_hi:[1,0]
	v_pk_mul_f32 v[0:1], v[0:1], v[82:83] op_sel_hi:[1,0]
	s_waitcnt vmcnt(0)
	v_mov_b64_e32 v[26:27], v[158:159]
	v_mov_b64_e32 v[28:29], v[160:161]
	v_mov_b64_e32 v[60:61], v[162:163]
	v_mov_b64_e32 v[62:63], v[164:165]
	v_pk_add_f32 v[22:23], v[28:29], 1.0 op_sel_hi:[1,0]
	v_pk_add_f32 v[24:25], v[26:27], 1.0 op_sel_hi:[1,0]
	v_pk_fma_f32 v[18:19], v[22:23], v[18:19], v[62:63]
	v_pk_fma_f32 v[6:7], v[24:25], v[6:7], v[60:61]
	s_nop 0
	v_cvt_pk_bf16_f32 v6, v6, v7
	v_cvt_pk_bf16_f32 v7, v18, v19
	global_store_dwordx2 v[56:57], v[6:7], off offset:512
	v_pk_mul_f32 v[6:7], v[20:21], v[82:83] op_sel_hi:[1,0]
	v_pk_mul_f32 v[18:19], v[70:71], v[82:83] op_sel_hi:[1,0]
	v_mov_b64_e32 v[22:23], v[166:167]
	v_mov_b64_e32 v[24:25], v[168:169]
	v_mov_b64_e32 v[26:27], v[170:171]
	v_mov_b64_e32 v[28:29], v[172:173]
	v_pk_add_f32 v[20:21], v[24:25], 1.0 op_sel_hi:[1,0]
	v_pk_add_f32 v[22:23], v[22:23], 1.0 op_sel_hi:[1,0]
	v_pk_fma_f32 v[18:19], v[20:21], v[18:19], v[28:29]
	v_pk_fma_f32 v[6:7], v[22:23], v[6:7], v[26:27]
	s_nop 0
	v_cvt_pk_bf16_f32 v6, v6, v7
	v_cvt_pk_bf16_f32 v7, v18, v19
	global_store_dwordx2 v[56:57], v[6:7], off offset:1024
	v_pk_mul_f32 v[2:3], v[16:17], v[82:83] op_sel_hi:[1,0]
	v_pk_mul_f32 v[6:7], v[72:73], v[82:83] op_sel_hi:[1,0]
	v_mov_b64_e32 v[18:19], v[174:175]
	v_mov_b64_e32 v[20:21], v[176:177]
	v_mov_b64_e32 v[22:23], v[178:179]
	v_mov_b64_e32 v[24:25], v[180:181]
	v_pk_add_f32 v[16:17], v[20:21], 1.0 op_sel_hi:[1,0]
	v_pk_add_f32 v[18:19], v[18:19], 1.0 op_sel_hi:[1,0]
	v_pk_fma_f32 v[6:7], v[16:17], v[6:7], v[24:25]
	v_pk_fma_f32 v[2:3], v[18:19], v[2:3], v[22:23]
	v_add_co_u32_e32 v24, vcc, s69, v74
	v_cvt_pk_bf16_f32 v2, v2, v3
	v_cvt_pk_bf16_f32 v3, v6, v7
	global_store_dwordx2 v[56:57], v[2:3], off offset:1536
	v_addc_co_u32_e32 v25, vcc, 0, v75, vcc
	v_pk_mul_f32 v[2:3], v[12:13], v[82:83] op_sel_hi:[1,0]
	v_pk_mul_f32 v[6:7], v[14:15], v[82:83] op_sel_hi:[1,0]
	v_mov_b64_e32 v[16:17], v[182:183]
	v_mov_b64_e32 v[18:19], v[184:185]
	v_mov_b64_e32 v[20:21], v[186:187]
	v_mov_b64_e32 v[22:23], v[188:189]
	v_pk_add_f32 v[12:13], v[18:19], 1.0 op_sel_hi:[1,0]
	v_pk_add_f32 v[14:15], v[16:17], 1.0 op_sel_hi:[1,0]
	v_pk_fma_f32 v[6:7], v[12:13], v[6:7], v[22:23]
	v_pk_fma_f32 v[2:3], v[14:15], v[2:3], v[20:21]
	s_nop 0
	v_cvt_pk_bf16_f32 v2, v2, v3
	v_cvt_pk_bf16_f32 v3, v6, v7
	global_store_dwordx2 v[56:57], v[2:3], off offset:2048
	v_pk_mul_f32 v[2:3], v[8:9], v[82:83] op_sel_hi:[1,0]
	v_pk_mul_f32 v[6:7], v[10:11], v[82:83] op_sel_hi:[1,0]
	v_mov_b64_e32 v[12:13], v[190:191]
	v_mov_b64_e32 v[14:15], v[192:193]
	v_mov_b64_e32 v[16:17], v[194:195]
	v_mov_b64_e32 v[18:19], v[196:197]
	v_pk_add_f32 v[8:9], v[14:15], 1.0 op_sel_hi:[1,0]
	v_pk_add_f32 v[10:11], v[12:13], 1.0 op_sel_hi:[1,0]
	v_pk_fma_f32 v[6:7], v[8:9], v[6:7], v[18:19]
	v_pk_fma_f32 v[2:3], v[10:11], v[2:3], v[16:17]
	s_nop 0
	v_cvt_pk_bf16_f32 v2, v2, v3
	v_cvt_pk_bf16_f32 v3, v6, v7
	global_store_dwordx2 v[56:57], v[2:3], off offset:2560
	v_pk_mul_f32 v[2:3], v[4:5], v[82:83] op_sel_hi:[1,0]
	v_pk_mul_f32 v[4:5], v[78:79], v[82:83] op_sel_hi:[1,0]
	v_mov_b64_e32 v[6:7], v[198:199]
	v_mov_b64_e32 v[8:9], v[200:201]
	v_mov_b64_e32 v[10:11], v[202:203]
	v_mov_b64_e32 v[12:13], v[204:205]
	v_pk_add_f32 v[8:9], v[8:9], 1.0 op_sel_hi:[1,0]
	v_pk_add_f32 v[6:7], v[6:7], 1.0 op_sel_hi:[1,0]
	v_pk_fma_f32 v[4:5], v[8:9], v[4:5], v[12:13]
	v_pk_fma_f32 v[2:3], v[6:7], v[2:3], v[10:11]
	v_pk_mul_f32 v[10:11], v[80:81], v[82:83] op_sel_hi:[1,0]
	v_cvt_pk_bf16_f32 v2, v2, v3
	v_cvt_pk_bf16_f32 v3, v4, v5
	global_store_dwordx2 v[56:57], v[2:3], off offset:3072
	v_mov_b64_e32 v[2:3], v[224:225]
	v_mov_b64_e32 v[4:5], v[226:227]
	v_mov_b64_e32 v[6:7], v[228:229]
	v_mov_b64_e32 v[8:9], v[230:231]
	v_pk_add_f32 v[4:5], v[4:5], 1.0 op_sel_hi:[1,0]
	v_pk_add_f32 v[2:3], v[2:3], 1.0 op_sel_hi:[1,0]
	v_pk_fma_f32 v[4:5], v[4:5], v[10:11], v[8:9]
	v_pk_fma_f32 v[0:1], v[2:3], v[0:1], v[6:7]
	s_nop 0
	v_cvt_pk_bf16_f32 v0, v0, v1
	v_cvt_pk_bf16_f32 v1, v4, v5
	global_store_dwordx2 v[56:57], v[0:1], off offset:3584
	s_branch .LBB0_344
